# gate unit: row-major ds_write_b128 + ds_read_b64_tr_b16 for LN(v) tile; GEMM B epilogue: rs loads hoisted, per-block vmcnt(0) removed
# speedup vs baseline: 1.0159x; 1.0095x over previous
; __device__ __forceinline__ unsigned cvt_pk_bf16(float lo, float hi) { f32x2 v = {lo, hi}; bf16x2_t b = __builtin_convertvector(v, bf16x2_t); return __builtin_bit_cast(unsigned, b); }
;     __device__ __forceinline__ void operator()(const f32x4 (&acc)[2][2][4][2], const Unit& u, int wr, int wc, int fr, int fq) const {
;     ...
;             for (int m = 0; m < 4; ++m) { const int r = row0 + ai * HALF + m * 16; const float s = rs ? rs[r] * cs : cs; bf16_t* rowp = Z + (size_t)r * ldc + col0;
;                 const int seq = r >> sshift, pos = r & ((1 << sshift) - 1), tile = pos >> 6, kv = pos & 63;
; #pragma unroll
;                 for (int bj = 0; bj < 2; ++bj) { const f32x4 v0 = acc[ai][bj][m][0] * s, v1 = acc[ai][bj][m][1] * s; u32x4 w;
;                     w.x = cvt_pk_bf16(v0[0], v0[1]); w.y = cvt_pk_bf16(v0[2], v0[3]); w.z = cvt_pk_bf16(v1[0], v1[1]); w.w = cvt_pk_bf16(v1[2], v1[3]);
;                     if (kvt) { const int c = col0 + bj * HALF; int hd, off;
;                         if (colt < 2048) { const int cp = c - 1024, d = cp & 63; hd = (cp >> 6) & 7; off = (cp >> 9) * 8192 + kv * 128 + (((d >> 3) ^ ((kv >> 1) & 7)) << 4); }
;                         else { const int cp = c - 2048, d = cp & 127; hd = cp >> 7; off = 16384 + (d >> 5) * 4096 + kv * 64 + (((d >> 3) & 3) << 4); }
;                         *(u32x4*)(KV + ((size_t)((((seq << 3) + hd) << (sshift - 6)) + tile) << 15) + off) = w; }
;                     else *(u32x4*)(rowp + bj * HALF) = w; } }
.LBB0_94:
	v_lshl_add_u32 v130, s8, 8, v143
	v_ashrrev_i32_e32 v131, 31, v130
	v_lshl_add_u64 v[132:133], v[130:131], 2, s[72:73]
	global_load_dword v162, v[132:133], off
	global_load_dword v163, v[132:133], off offset:64
	global_load_dword v164, v[132:133], off offset:128
	global_load_dword v165, v[132:133], off offset:192
	global_load_dword v166, v[132:133], off offset:512
	global_load_dword v167, v[132:133], off offset:576
	global_load_dword v168, v[132:133], off offset:640
	global_load_dword v169, v[132:133], off offset:704
	s_lshl_b32 s54, s55, 8
	v_mov_b64_e32 v[136:137], s[70:71]
	s_cmp_lt_i32 s55, 4
	v_mad_i64_i32 v[136:137], s[6:7], v130, s35, v[136:137]
	s_cselect_b64 vcc, -1, 0
	v_cndmask_b32_e32 v131, 1.0, v208, vcc
	s_add_i32 s6, s55, -4
	v_or_b32_e32 v134, s54, v144
	s_cmp_gt_u32 s6, 7
	v_ashrrev_i32_e32 v135, 31, v134
	s_cselect_b64 s[26:27], -1, 0
	s_cmp_lt_u32 s55, 8
	s_mov_b64 s[8:9], -1
	v_lshl_add_u64 v[136:137], v[134:135], 1, v[136:137]
	s_cselect_b64 s[6:7], -1, 0
	s_and_b64 vcc, exec, s[26:27]
	s_waitcnt vmcnt(0)
	v_mul_f32_e32 v138, v131, v162
	v_pk_mul_f32 v[128:129], v[128:129], v[138:139] op_sel_hi:[1,0]
	v_pk_mul_f32 v[126:127], v[126:127], v[138:139] op_sel_hi:[1,0]
	v_pk_mul_f32 v[154:155], v[124:125], v[138:139] op_sel_hi:[1,0]
	v_pk_mul_f32 v[124:125], v[122:123], v[138:139] op_sel_hi:[1,0]
	v_cvt_pk_bf16_f32 v122, v126, v127
	v_cvt_pk_bf16_f32 v123, v128, v129
	v_cvt_pk_bf16_f32 v124, v124, v125
	v_cvt_pk_bf16_f32 v125, v154, v155
	s_cbranch_vccz .LBB0_96
	global_store_dwordx4 v[136:137], v[122:125], off
	s_mov_b64 s[8:9], 0

; __device__ __forceinline__ unsigned cvt_pk_bf16(float lo, float hi) { f32x2 v = {lo, hi}; bf16x2_t b = __builtin_convertvector(v, bf16x2_t); return __builtin_bit_cast(unsigned, b); }
;     __device__ __forceinline__ void operator()(const f32x4 (&acc)[2][2][4][2], const Unit& u, int wr, int wc, int fr, int fq) const {
;     ...
;             for (int m = 0; m < 4; ++m) { const int r = row0 + ai * HALF + m * 16; const float s = rs ? rs[r] * cs : cs; bf16_t* rowp = Z + (size_t)r * ldc + col0;
;                 const int seq = r >> sshift, pos = r & ((1 << sshift) - 1), tile = pos >> 6, kv = pos & 63;
; #pragma unroll
;                 for (int bj = 0; bj < 2; ++bj) { const f32x4 v0 = acc[ai][bj][m][0] * s, v1 = acc[ai][bj][m][1] * s; u32x4 w;
;                     w.x = cvt_pk_bf16(v0[0], v0[1]); w.y = cvt_pk_bf16(v0[2], v0[3]); w.z = cvt_pk_bf16(v1[0], v1[1]); w.w = cvt_pk_bf16(v1[2], v1[3]);
;                     if (kvt) { const int c = col0 + bj * HALF; int hd, off;
;                         if (colt < 2048) { const int cp = c - 1024, d = cp & 63; hd = (cp >> 6) & 7; off = (cp >> 9) * 8192 + kv * 128 + (((d >> 3) ^ ((kv >> 1) & 7)) << 4); }
;                         else { const int cp = c - 2048, d = cp & 127; hd = cp >> 7; off = 16384 + (d >> 5) * 4096 + kv * 64 + (((d >> 3) & 3) << 4); }
;                         *(u32x4*)(KV + ((size_t)((((seq << 3) + hd) << (sshift - 6)) + tile) << 15) + off) = w; }
;                     else *(u32x4*)(rowp + bj * HALF) = w; } }
.LBB0_102:
	v_or_b32_e32 v118, 16, v130
	v_ashrrev_i32_e32 v119, 31, v118
	v_lshl_add_u64 v[114:115], v[118:119], 2, s[72:73]
	v_mov_b64_e32 v[114:115], s[70:71]
	v_mad_i64_i32 v[114:115], s[26:27], v118, s35, v[114:115]
	s_and_b64 vcc, exec, s[8:9]
	v_lshl_add_u64 v[114:115], v[134:135], 1, v[114:115]
	s_mov_b64 s[26:27], -1
	v_mul_f32_e32 v116, v131, v163
	v_pk_mul_f32 v[112:113], v[112:113], v[116:117] op_sel_hi:[1,0]
	v_pk_mul_f32 v[110:111], v[110:111], v[116:117] op_sel_hi:[1,0]
	v_pk_mul_f32 v[120:121], v[108:109], v[116:117] op_sel_hi:[1,0]
	v_pk_mul_f32 v[108:109], v[106:107], v[116:117] op_sel_hi:[1,0]
	v_cvt_pk_bf16_f32 v106, v110, v111
	v_cvt_pk_bf16_f32 v107, v112, v113
	v_cvt_pk_bf16_f32 v108, v108, v109
	v_cvt_pk_bf16_f32 v109, v120, v121
	s_cbranch_vccnz .LBB0_104
	s_mov_b64 s[26:27], 0
	global_store_dwordx4 v[114:115], v[106:109], off

; __device__ __forceinline__ unsigned cvt_pk_bf16(float lo, float hi) { f32x2 v = {lo, hi}; bf16x2_t b = __builtin_convertvector(v, bf16x2_t); return __builtin_bit_cast(unsigned, b); }
;     __device__ __forceinline__ void operator()(const f32x4 (&acc)[2][2][4][2], const Unit& u, int wr, int wc, int fr, int fq) const {
;     ...
;             for (int m = 0; m < 4; ++m) { const int r = row0 + ai * HALF + m * 16; const float s = rs ? rs[r] * cs : cs; bf16_t* rowp = Z + (size_t)r * ldc + col0;
;                 const int seq = r >> sshift, pos = r & ((1 << sshift) - 1), tile = pos >> 6, kv = pos & 63;
; #pragma unroll
;                 for (int bj = 0; bj < 2; ++bj) { const f32x4 v0 = acc[ai][bj][m][0] * s, v1 = acc[ai][bj][m][1] * s; u32x4 w;
;                     w.x = cvt_pk_bf16(v0[0], v0[1]); w.y = cvt_pk_bf16(v0[2], v0[3]); w.z = cvt_pk_bf16(v1[0], v1[1]); w.w = cvt_pk_bf16(v1[2], v1[3]);
;                     if (kvt) { const int c = col0 + bj * HALF; int hd, off;
;                         if (colt < 2048) { const int cp = c - 1024, d = cp & 63; hd = (cp >> 6) & 7; off = (cp >> 9) * 8192 + kv * 128 + (((d >> 3) ^ ((kv >> 1) & 7)) << 4); }
;                         else { const int cp = c - 2048, d = cp & 127; hd = cp >> 7; off = 16384 + (d >> 5) * 4096 + kv * 64 + (((d >> 3) & 3) << 4); }
;                         *(u32x4*)(KV + ((size_t)((((seq << 3) + hd) << (sshift - 6)) + tile) << 15) + off) = w; }
;                     else *(u32x4*)(rowp + bj * HALF) = w; } }
.LBB0_110:
	v_or_b32_e32 v102, 32, v130
	v_ashrrev_i32_e32 v103, 31, v102
	v_lshl_add_u64 v[98:99], v[102:103], 2, s[72:73]
	v_mov_b64_e32 v[98:99], s[70:71]
	v_mad_i64_i32 v[98:99], s[26:27], v102, s35, v[98:99]
	s_and_b64 vcc, exec, s[8:9]
	v_lshl_add_u64 v[98:99], v[134:135], 1, v[98:99]
	s_mov_b64 s[26:27], -1
	v_mul_f32_e32 v100, v131, v164
	v_pk_mul_f32 v[96:97], v[96:97], v[100:101] op_sel_hi:[1,0]
	v_pk_mul_f32 v[94:95], v[94:95], v[100:101] op_sel_hi:[1,0]
	v_pk_mul_f32 v[104:105], v[92:93], v[100:101] op_sel_hi:[1,0]
	v_pk_mul_f32 v[92:93], v[90:91], v[100:101] op_sel_hi:[1,0]
	v_cvt_pk_bf16_f32 v90, v94, v95
	v_cvt_pk_bf16_f32 v91, v96, v97
	v_cvt_pk_bf16_f32 v92, v92, v93
	v_cvt_pk_bf16_f32 v93, v104, v105
	s_cbranch_vccnz .LBB0_112
	s_mov_b64 s[26:27], 0
	global_store_dwordx4 v[98:99], v[90:93], off

; __device__ __forceinline__ unsigned cvt_pk_bf16(float lo, float hi) { f32x2 v = {lo, hi}; bf16x2_t b = __builtin_convertvector(v, bf16x2_t); return __builtin_bit_cast(unsigned, b); }
;     __device__ __forceinline__ void operator()(const f32x4 (&acc)[2][2][4][2], const Unit& u, int wr, int wc, int fr, int fq) const {
;     ...
;             for (int m = 0; m < 4; ++m) { const int r = row0 + ai * HALF + m * 16; const float s = rs ? rs[r] * cs : cs; bf16_t* rowp = Z + (size_t)r * ldc + col0;
;                 const int seq = r >> sshift, pos = r & ((1 << sshift) - 1), tile = pos >> 6, kv = pos & 63;
; #pragma unroll
;                 for (int bj = 0; bj < 2; ++bj) { const f32x4 v0 = acc[ai][bj][m][0] * s, v1 = acc[ai][bj][m][1] * s; u32x4 w;
;                     w.x = cvt_pk_bf16(v0[0], v0[1]); w.y = cvt_pk_bf16(v0[2], v0[3]); w.z = cvt_pk_bf16(v1[0], v1[1]); w.w = cvt_pk_bf16(v1[2], v1[3]);
;                     if (kvt) { const int c = col0 + bj * HALF; int hd, off;
;                         if (colt < 2048) { const int cp = c - 1024, d = cp & 63; hd = (cp >> 6) & 7; off = (cp >> 9) * 8192 + kv * 128 + (((d >> 3) ^ ((kv >> 1) & 7)) << 4); }
;                         else { const int cp = c - 2048, d = cp & 127; hd = cp >> 7; off = 16384 + (d >> 5) * 4096 + kv * 64 + (((d >> 3) & 3) << 4); }
;                         *(u32x4*)(KV + ((size_t)((((seq << 3) + hd) << (sshift - 6)) + tile) << 15) + off) = w; }
;                     else *(u32x4*)(rowp + bj * HALF) = w; } }
.LBB0_118:
	v_or_b32_e32 v86, 48, v130
	v_ashrrev_i32_e32 v87, 31, v86
	v_lshl_add_u64 v[82:83], v[86:87], 2, s[72:73]
	v_mov_b64_e32 v[82:83], s[70:71]
	v_mad_i64_i32 v[82:83], s[26:27], v86, s35, v[82:83]
	s_and_b64 vcc, exec, s[8:9]
	v_lshl_add_u64 v[82:83], v[134:135], 1, v[82:83]
	s_mov_b64 s[26:27], -1
	v_mul_f32_e32 v84, v131, v165
	v_pk_mul_f32 v[80:81], v[80:81], v[84:85] op_sel_hi:[1,0]
	v_pk_mul_f32 v[78:79], v[78:79], v[84:85] op_sel_hi:[1,0]
	v_pk_mul_f32 v[88:89], v[76:77], v[84:85] op_sel_hi:[1,0]
	v_pk_mul_f32 v[76:77], v[74:75], v[84:85] op_sel_hi:[1,0]
	v_cvt_pk_bf16_f32 v74, v78, v79
	v_cvt_pk_bf16_f32 v75, v80, v81
	v_cvt_pk_bf16_f32 v76, v76, v77
	v_cvt_pk_bf16_f32 v77, v88, v89
	s_cbranch_vccnz .LBB0_120
	s_mov_b64 s[26:27], 0
	global_store_dwordx4 v[82:83], v[74:77], off

; __device__ __forceinline__ unsigned cvt_pk_bf16(float lo, float hi) { f32x2 v = {lo, hi}; bf16x2_t b = __builtin_convertvector(v, bf16x2_t); return __builtin_bit_cast(unsigned, b); }
;     __device__ __forceinline__ void operator()(const f32x4 (&acc)[2][2][4][2], const Unit& u, int wr, int wc, int fr, int fq) const {
;     ...
;             for (int m = 0; m < 4; ++m) { const int r = row0 + ai * HALF + m * 16; const float s = rs ? rs[r] * cs : cs; bf16_t* rowp = Z + (size_t)r * ldc + col0;
;                 const int seq = r >> sshift, pos = r & ((1 << sshift) - 1), tile = pos >> 6, kv = pos & 63;
; #pragma unroll
;                 for (int bj = 0; bj < 2; ++bj) { const f32x4 v0 = acc[ai][bj][m][0] * s, v1 = acc[ai][bj][m][1] * s; u32x4 w;
;                     w.x = cvt_pk_bf16(v0[0], v0[1]); w.y = cvt_pk_bf16(v0[2], v0[3]); w.z = cvt_pk_bf16(v1[0], v1[1]); w.w = cvt_pk_bf16(v1[2], v1[3]);
;                     if (kvt) { const int c = col0 + bj * HALF; int hd, off;
;                         if (colt < 2048) { const int cp = c - 1024, d = cp & 63; hd = (cp >> 6) & 7; off = (cp >> 9) * 8192 + kv * 128 + (((d >> 3) ^ ((kv >> 1) & 7)) << 4); }
;                         else { const int cp = c - 2048, d = cp & 127; hd = cp >> 7; off = 16384 + (d >> 5) * 4096 + kv * 64 + (((d >> 3) & 3) << 4); }
;                         *(u32x4*)(KV + ((size_t)((((seq << 3) + hd) << (sshift - 6)) + tile) << 15) + off) = w; }
;                     else *(u32x4*)(rowp + bj * HALF) = w; } }
.LBB0_126:
	s_nop 0
	s_nop 0
	v_add_u32_e32 v69, 0x80, v130
	v_mov_b64_e32 v[66:67], s[70:71]
	v_mad_i64_i32 v[66:67], s[26:27], v69, s35, v[66:67]
	s_and_b64 vcc, exec, s[8:9]
	v_lshl_add_u64 v[66:67], v[134:135], 1, v[66:67]
	s_mov_b64 s[26:27], -1
	v_mul_f32_e32 v68, v131, v166
	v_pk_mul_f32 v[64:65], v[64:65], v[68:69] op_sel_hi:[1,0]
	v_pk_mul_f32 v[62:63], v[62:63], v[68:69] op_sel_hi:[1,0]
	v_pk_mul_f32 v[70:71], v[60:61], v[68:69] op_sel_hi:[1,0]
	v_pk_mul_f32 v[60:61], v[58:59], v[68:69] op_sel_hi:[1,0]
	v_cvt_pk_bf16_f32 v58, v62, v63
	v_cvt_pk_bf16_f32 v59, v64, v65
	v_cvt_pk_bf16_f32 v60, v60, v61
	v_cvt_pk_bf16_f32 v61, v70, v71
	s_cbranch_vccnz .LBB0_128
	s_mov_b64 s[26:27], 0
	global_store_dwordx4 v[66:67], v[58:61], off

; __device__ __forceinline__ unsigned cvt_pk_bf16(float lo, float hi) { f32x2 v = {lo, hi}; bf16x2_t b = __builtin_convertvector(v, bf16x2_t); return __builtin_bit_cast(unsigned, b); }
;     __device__ __forceinline__ void operator()(const f32x4 (&acc)[2][2][4][2], const Unit& u, int wr, int wc, int fr, int fq) const {
;     ...
;             for (int m = 0; m < 4; ++m) { const int r = row0 + ai * HALF + m * 16; const float s = rs ? rs[r] * cs : cs; bf16_t* rowp = Z + (size_t)r * ldc + col0;
;                 const int seq = r >> sshift, pos = r & ((1 << sshift) - 1), tile = pos >> 6, kv = pos & 63;
; #pragma unroll
;                 for (int bj = 0; bj < 2; ++bj) { const f32x4 v0 = acc[ai][bj][m][0] * s, v1 = acc[ai][bj][m][1] * s; u32x4 w;
;                     w.x = cvt_pk_bf16(v0[0], v0[1]); w.y = cvt_pk_bf16(v0[2], v0[3]); w.z = cvt_pk_bf16(v1[0], v1[1]); w.w = cvt_pk_bf16(v1[2], v1[3]);
;                     if (kvt) { const int c = col0 + bj * HALF; int hd, off;
;                         if (colt < 2048) { const int cp = c - 1024, d = cp & 63; hd = (cp >> 6) & 7; off = (cp >> 9) * 8192 + kv * 128 + (((d >> 3) ^ ((kv >> 1) & 7)) << 4); }
;                         else { const int cp = c - 2048, d = cp & 127; hd = cp >> 7; off = 16384 + (d >> 5) * 4096 + kv * 64 + (((d >> 3) & 3) << 4); }
;                         *(u32x4*)(KV + ((size_t)((((seq << 3) + hd) << (sshift - 6)) + tile) << 15) + off) = w; }
;                     else *(u32x4*)(rowp + bj * HALF) = w; } }
.LBB0_134:
	s_nop 0
	s_nop 0
	v_add_u32_e32 v53, 0x90, v130
	v_mov_b64_e32 v[50:51], s[70:71]
	v_mad_i64_i32 v[50:51], s[26:27], v53, s35, v[50:51]
	s_and_b64 vcc, exec, s[8:9]
	v_lshl_add_u64 v[50:51], v[134:135], 1, v[50:51]
	s_mov_b64 s[26:27], -1
	v_mul_f32_e32 v52, v131, v167
	v_pk_mul_f32 v[48:49], v[48:49], v[52:53] op_sel_hi:[1,0]
	v_pk_mul_f32 v[46:47], v[46:47], v[52:53] op_sel_hi:[1,0]
	v_pk_mul_f32 v[54:55], v[44:45], v[52:53] op_sel_hi:[1,0]
	v_pk_mul_f32 v[44:45], v[42:43], v[52:53] op_sel_hi:[1,0]
	v_cvt_pk_bf16_f32 v42, v46, v47
	v_cvt_pk_bf16_f32 v43, v48, v49
	v_cvt_pk_bf16_f32 v44, v44, v45
	v_cvt_pk_bf16_f32 v45, v54, v55
	s_cbranch_vccnz .LBB0_136
	s_mov_b64 s[26:27], 0
	global_store_dwordx4 v[50:51], v[42:45], off

; __device__ __forceinline__ unsigned cvt_pk_bf16(float lo, float hi) { f32x2 v = {lo, hi}; bf16x2_t b = __builtin_convertvector(v, bf16x2_t); return __builtin_bit_cast(unsigned, b); }
;     __device__ __forceinline__ void operator()(const f32x4 (&acc)[2][2][4][2], const Unit& u, int wr, int wc, int fr, int fq) const {
;     ...
;             for (int m = 0; m < 4; ++m) { const int r = row0 + ai * HALF + m * 16; const float s = rs ? rs[r] * cs : cs; bf16_t* rowp = Z + (size_t)r * ldc + col0;
;                 const int seq = r >> sshift, pos = r & ((1 << sshift) - 1), tile = pos >> 6, kv = pos & 63;
; #pragma unroll
;                 for (int bj = 0; bj < 2; ++bj) { const f32x4 v0 = acc[ai][bj][m][0] * s, v1 = acc[ai][bj][m][1] * s; u32x4 w;
;                     w.x = cvt_pk_bf16(v0[0], v0[1]); w.y = cvt_pk_bf16(v0[2], v0[3]); w.z = cvt_pk_bf16(v1[0], v1[1]); w.w = cvt_pk_bf16(v1[2], v1[3]);
;                     if (kvt) { const int c = col0 + bj * HALF; int hd, off;
;                         if (colt < 2048) { const int cp = c - 1024, d = cp & 63; hd = (cp >> 6) & 7; off = (cp >> 9) * 8192 + kv * 128 + (((d >> 3) ^ ((kv >> 1) & 7)) << 4); }
;                         else { const int cp = c - 2048, d = cp & 127; hd = cp >> 7; off = 16384 + (d >> 5) * 4096 + kv * 64 + (((d >> 3) & 3) << 4); }
;                         *(u32x4*)(KV + ((size_t)((((seq << 3) + hd) << (sshift - 6)) + tile) << 15) + off) = w; }
;                     else *(u32x4*)(rowp + bj * HALF) = w; } }
.LBB0_142:
	s_nop 0
	s_nop 0
	v_add_u32_e32 v37, 0xa0, v130
	v_mov_b64_e32 v[34:35], s[70:71]
	v_mad_i64_i32 v[34:35], s[26:27], v37, s35, v[34:35]
	s_and_b64 vcc, exec, s[8:9]
	v_lshl_add_u64 v[34:35], v[134:135], 1, v[34:35]
	s_mov_b64 s[26:27], -1
	v_mul_f32_e32 v36, v131, v168
	v_pk_mul_f32 v[32:33], v[32:33], v[36:37] op_sel_hi:[1,0]
	v_pk_mul_f32 v[30:31], v[30:31], v[36:37] op_sel_hi:[1,0]
	v_pk_mul_f32 v[38:39], v[28:29], v[36:37] op_sel_hi:[1,0]
	v_pk_mul_f32 v[28:29], v[26:27], v[36:37] op_sel_hi:[1,0]
	v_cvt_pk_bf16_f32 v26, v30, v31
	v_cvt_pk_bf16_f32 v27, v32, v33
	v_cvt_pk_bf16_f32 v28, v28, v29
	v_cvt_pk_bf16_f32 v29, v38, v39
	s_cbranch_vccnz .LBB0_144
	s_mov_b64 s[26:27], 0
	global_store_dwordx4 v[34:35], v[26:29], off

; __device__ __forceinline__ unsigned cvt_pk_bf16(float lo, float hi) { f32x2 v = {lo, hi}; bf16x2_t b = __builtin_convertvector(v, bf16x2_t); return __builtin_bit_cast(unsigned, b); }
;     __device__ __forceinline__ void operator()(const f32x4 (&acc)[2][2][4][2], const Unit& u, int wr, int wc, int fr, int fq) const {
;     ...
;             for (int m = 0; m < 4; ++m) { const int r = row0 + ai * HALF + m * 16; const float s = rs ? rs[r] * cs : cs; bf16_t* rowp = Z + (size_t)r * ldc + col0;
;                 const int seq = r >> sshift, pos = r & ((1 << sshift) - 1), tile = pos >> 6, kv = pos & 63;
; #pragma unroll
;                 for (int bj = 0; bj < 2; ++bj) { const f32x4 v0 = acc[ai][bj][m][0] * s, v1 = acc[ai][bj][m][1] * s; u32x4 w;
;                     w.x = cvt_pk_bf16(v0[0], v0[1]); w.y = cvt_pk_bf16(v0[2], v0[3]); w.z = cvt_pk_bf16(v1[0], v1[1]); w.w = cvt_pk_bf16(v1[2], v1[3]);
;                     if (kvt) { const int c = col0 + bj * HALF; int hd, off;
;                         if (colt < 2048) { const int cp = c - 1024, d = cp & 63; hd = (cp >> 6) & 7; off = (cp >> 9) * 8192 + kv * 128 + (((d >> 3) ^ ((kv >> 1) & 7)) << 4); }
;                         else { const int cp = c - 2048, d = cp & 127; hd = cp >> 7; off = 16384 + (d >> 5) * 4096 + kv * 64 + (((d >> 3) & 3) << 4); }
;                         *(u32x4*)(KV + ((size_t)((((seq << 3) + hd) << (sshift - 6)) + tile) << 15) + off) = w; }
;                     else *(u32x4*)(rowp + bj * HALF) = w; } }
.LBB0_150:
	s_nop 0
	s_nop 0
	v_add_u32_e32 v21, 0xb0, v130
	s_and_b64 vcc, exec, s[8:9]
	v_mul_f32_e32 v20, v131, v169
	v_mov_b64_e32 v[18:19], s[70:71]
	v_mad_i64_i32 v[18:19], s[26:27], v21, s35, v[18:19]
	v_pk_mul_f32 v[16:17], v[16:17], v[20:21] op_sel_hi:[1,0]
	v_pk_mul_f32 v[14:15], v[14:15], v[20:21] op_sel_hi:[1,0]
	v_pk_mul_f32 v[22:23], v[12:13], v[20:21] op_sel_hi:[1,0]
	v_pk_mul_f32 v[12:13], v[10:11], v[20:21] op_sel_hi:[1,0]
	v_lshl_add_u64 v[18:19], v[134:135], 1, v[18:19]
	v_cvt_pk_bf16_f32 v10, v14, v15
	v_cvt_pk_bf16_f32 v11, v16, v17
	v_cvt_pk_bf16_f32 v12, v12, v13
	v_cvt_pk_bf16_f32 v13, v22, v23
	s_mov_b64 s[26:27], -1
	s_cbranch_vccnz .LBB0_152
	s_mov_b64 s[26:27], 0
	global_store_dwordx4 v[18:19], v[10:13], off

; __device__ __forceinline__ float bf_lo(unsigned w) { return __uint_as_float(w << 16); }
; __device__ __forceinline__ float bf_hi(unsigned w) { return __uint_as_float(w & 0xffff0000u); }
; __device__ __forceinline__ unsigned f2bf(float f) { unsigned u = __builtin_bit_cast(unsigned, f); return (u + 0x7fffu + ((u >> 16) & 1u)) >> 16; }
; __device__ __forceinline__ void gate_unit(LAS unsigned char* lds, bf16_t* Zg, int ch, const bf16_t* wsb, const float* ln_g, const float* ln_b, const float* b_s, bool dostore = true) {
;     ...
;     __syncthreads();
;     const int pt = wid >> 1, kt0 = 2 * (wid & 1);
;     for (int g = 0; g < 8; ++g) {
; #pragma unroll
;         for (int i = 0; i < 4; ++i) { const int p = tid + 512 * i, q = p >> 4, c = p & 15; const int col = g * 128 + c * 8;
;             const u32x4 w = *(const u32x4*)(Zc + (size_t)q * ZLD + COL_VB + col);
;             const float mean = stats[q * 2], rstd = stats[q * 2 + 1];
;             const f32x4 g0 = *(const f32x4*)(ln_g + col), g1 = *(const f32x4*)(ln_g + col + 4), b0 = *(const f32x4*)(ln_b + col), b1 = *(const f32x4*)(ln_b + col + 4);
;             float v[8] = {bf_lo(w.x), bf_hi(w.x), bf_lo(w.y), bf_hi(w.y), bf_lo(w.z), bf_hi(w.z), bf_lo(w.w), bf_hi(w.w)};
;             const float gg[8] = {g0.x, g0.y, g0.z, g0.w, g1.x, g1.y, g1.z, g1.w}, bb[8] = {b0.x, b0.y, b0.z, b0.w, b1.x, b1.y, b1.z, b1.w};
; #pragma unroll
;             for (int e = 0; e < 8; ++e) vnT[(c * 8 + e) * 136 + q] = (bf16_t)f2bf((v[e] - mean) * rstd * gg[e] + bb[e]); }
.LBB0_182:
	s_or_b64 exec, exec, s[74:75]
	v_lshlrev_b32_e32 v2, 3, v6
	s_lshr_b32 s4, s10, 5
	v_and_b32_e32 v4, 0x78, v2
	s_ashr_i32 s10, s10, 2
	v_ashrrev_i32_e32 v14, 4, v6
	v_lshrrev_b32_e32 v0, 5, v0
	s_and_b32 s16, s4, 2
	s_and_b32 s4, s10, 0xffffffe0
	v_lshl_add_u32 v37, v4, 2, 0
	v_lshl_add_u32 v36, v14, 3, 0
	v_lshl_or_b32 v34, v0, 2, s4
	s_waitcnt lgkmcnt(1)
	v_mad_u64_u32 v[2:3], s[4:5], v14, -6, v[36:37]
	v_mul_u32_u24_e32 v3, 0x110, v4
	v_add_u32_e32 v4, 0x200, v6
	v_ashrrev_i32_e32 v17, 4, v4
	v_lshl_add_u32 v38, v17, 3, 0
	s_waitcnt lgkmcnt(0)
	v_mad_u64_u32 v[4:5], s[4:5], v17, -6, v[38:39]
	v_add_u32_e32 v5, 0x400, v6
	v_ashrrev_i32_e32 v5, 4, v5
	v_lshl_add_u32 v40, v5, 3, 0
	v_mad_u64_u32 v[8:9], s[4:5], v5, -6, v[40:41]
	v_add_u32_e32 v9, 0x600, v6
	v_ashrrev_i32_e32 v9, 4, v9
	v_lshl_add_u32 v42, v9, 3, 0
	v_and_b32_e32 v7, 31, v6
	v_mad_u64_u32 v[10:11], s[4:5], v9, -6, v[42:43]
	v_lshl_add_u32 v16, v0, 4, 0
	v_lshl_add_u32 v0, v7, 2, 0
	s_or_b32 s4, s16, 1
	v_lshl_or_b32 v12, s4, 5, v7
	v_lshl_add_u32 v21, s4, 7, v0
	s_lshl_b32 s4, s10, 7
	s_and_b32 s4, s4, 0xfffff000
	v_mul_u32_u24_e32 v18, 0x110, v12
	v_lshl_or_b32 v12, v7, 7, s4
	v_lshl_add_u32 v19, s16, 7, v0
	v_and_b32_e32 v0, 32, v6
	v_ashrrev_i32_e32 v13, 31, v12
	v_lshrrev_b32_e32 v0, 1, v0
	v_lshlrev_b64 v[12:13], 1, v[12:13]
	v_or_b32_e32 v12, v12, v0
	v_lshl_add_u64 v[12:13], s[72:73], 0, v[12:13]
	s_mov_b64 s[4:5], 0x1800000
	v_lshl_add_u64 v[44:45], v[12:13], 0, s[4:5]
	v_mov_b64_e32 v[12:13], s[8:9]
	v_mul_lo_u32 v39, v14, s25
	v_mad_i64_i32 v[12:13], s[4:5], v14, s35, v[12:13]
	v_and_b32_e32 v14, 15, v6
	v_lshlrev_b32_e32 v0, 4, v14
	v_lshl_or_b32 v11, s16, 5, v7
	v_lshl_add_u64 v[6:7], v[12:13], 0, v[0:1]
	v_lshl_add_u64 v[46:47], s[26:27], 0, v[6:7]
	v_mov_b64_e32 v[6:7], s[6:7]
	v_mad_i64_i32 v[12:13], s[4:5], v9, s35, v[6:7]
	v_lshl_add_u64 v[12:13], v[12:13], 0, v[0:1]
	v_lshl_add_u64 v[48:49], s[26:27], 0, v[12:13]
	v_lshlrev_b32_e32 v12, 5, v14
	v_mov_b32_e32 v13, v1
	v_lshl_add_u64 v[14:15], s[70:71], 0, v[12:13]
	v_lshl_add_u64 v[50:51], v[14:15], 0, 16
	v_mad_i64_i32 v[14:15], s[4:5], v5, s35, v[6:7]
	v_mad_i64_i32 v[6:7], s[4:5], v17, s35, v[6:7]
	v_mul_u32_u24_e32 v11, 0x110, v11
	v_mul_lo_u32 v20, v34, s25
	v_add_u32_e32 v22, 0x8400, v39
	v_lshl_add_u64 v[14:15], v[14:15], 0, v[0:1]
	v_lshl_add_u64 v[12:13], s[68:69], 0, v[12:13]
	v_lshl_add_u64 v[6:7], v[6:7], 0, v[0:1]
	v_lshl_add_u64 v[52:53], s[26:27], 0, v[14:15]
	v_lshl_add_u64 v[54:55], v[12:13], 0, 16
	v_lshl_add_u64 v[56:57], s[26:27], 0, v[6:7]
	s_mov_b64 s[4:5], 0
	v_add_u32_e32 v0, v2, v3
	v_add_u32_e32 v41, v4, v3
	v_add_u32_e32 v43, v8, v3
	v_add_u32_e32 v62, v10, v3
	v_add_u32_e32 v63, v16, v11
	v_add_u32_e32 v64, v16, v18
	v_add_u32_e32 v65, v19, v20
	v_add_u32_e32 v66, v21, v20
	v_add_u32_e32 v67, v37, v22
	v_lshrrev_b32_e32 v176, 4, v204
	v_mul_u32_u24_e32 v176, 0x120, v176
	v_and_b32_e32 v177, 15, v204
	v_lshl_add_u32 v176, v177, 4, v176
	v_and_b32_e32 v177, 63, v204
	v_lshrrev_b32_e32 v178, 5, v177
	v_bfe_u32 v179, v177, 2, 2
	v_lshl_add_u32 v178, v178, 3, v179
	v_mul_u32_u24_e32 v178, 0x120, v178
	v_bfe_u32 v179, v177, 4, 1
	v_lshl_add_u32 v178, v179, 5, v178
	v_and_b32_e32 v179, 3, v177
	v_lshl_add_u32 v178, v179, 3, v178
	v_lshl_add_u32 v177, s16, 6, v178
	s_barrier
.LBB0_183:
	v_lshl_add_u64 v[58:59], v[46:47], 0, s[4:5]
	v_add_co_u32_e32 v60, vcc, 0x5a02000, v58
	ds_read_b64 v[22:23], v36
	s_nop 0
	v_addc_co_u32_e32 v61, vcc, 0, v59, vcc
	global_load_dwordx4 v[18:21], v[60:61], off offset:2048
	global_load_dwordx4 v[2:5], v[50:51], off
	global_load_dwordx4 v[10:13], v[50:51], off offset:-16
	global_load_dwordx4 v[6:9], v[54:55], off
	global_load_dwordx4 v[14:17], v[54:55], off offset:-16
	v_ashrrev_i32_e32 v35, 31, v34
	s_mov_b32 s10, 0x5a03000
	s_mov_b64 s[16:17], 0x8000
	v_lshl_add_u64 v[50:51], v[50:51], 0, s[60:61]
	v_lshl_add_u64 v[54:55], v[54:55], 0, s[60:61]
	v_lshl_add_u64 v[80:81], v[56:57], 0, s[4:5]
	global_load_dwordx4 v[80:83], v[80:81], off
	v_lshl_add_u64 v[84:85], v[52:53], 0, s[4:5]
	global_load_dwordx4 v[84:87], v[84:85], off
	v_lshl_add_u64 v[88:89], v[48:49], 0, s[4:5]
	global_load_dwordx4 v[88:91], v[88:89], off
	global_load_dwordx4 v[92:95], v[44:45], off
	global_load_dwordx4 v[96:99], v[44:45], off offset:32
	global_load_dwordx4 v[100:103], v[44:45], off offset:64
	global_load_dwordx4 v[104:107], v[44:45], off offset:96
	global_load_dwordx4 v[108:111], v[44:45], off offset:128
	global_load_dwordx4 v[112:115], v[44:45], off offset:160
	global_load_dwordx4 v[116:119], v[44:45], off offset:192
	global_load_dwordx4 v[120:123], v[44:45], off offset:224
	v_lshl_add_u64 v[124:125], v[34:35], 2, s[20:21]
	global_load_dwordx4 v[126:129], v[124:125], off
	global_load_dwordx4 v[130:133], v[124:125], off offset:32
	global_load_dwordx4 v[134:137], v[124:125], off offset:64
	global_load_dwordx4 v[138:141], v[124:125], off offset:96
	v_add_co_u32_e32 v174, vcc, 0x5a03000, v58
	s_nop 1
	v_addc_co_u32_e32 v175, vcc, 0, v59, vcc
	global_load_dwordx4 v[142:145], v[174:175], off offset:-4096
	global_load_dwordx4 v[146:149], v[174:175], off
	v_add_co_u32_e32 v174, vcc, 0x5a93000, v58
	s_nop 1
	v_addc_co_u32_e32 v175, vcc, 0, v59, vcc
	global_load_dwordx4 v[150:153], v[174:175], off offset:-4096
	global_load_dwordx4 v[154:157], v[174:175], off
	v_add_co_u32_e32 v174, vcc, 0x5b23000, v58
	s_nop 1
	v_addc_co_u32_e32 v175, vcc, 0, v59, vcc
	global_load_dwordx4 v[158:161], v[174:175], off offset:-4096
	global_load_dwordx4 v[162:165], v[174:175], off
	v_add_co_u32_e32 v174, vcc, 0x5bb3000, v58
	s_nop 1
	v_addc_co_u32_e32 v175, vcc, 0, v59, vcc
	global_load_dwordx4 v[166:169], v[174:175], off offset:-4096
	global_load_dwordx4 v[170:173], v[174:175], off
	ds_read_b64 v[180:181], v38
	ds_read_b64 v[182:183], v40
	ds_read_b64 v[184:185], v42
	s_waitcnt vmcnt(23) lgkmcnt(3)
; __device__ __forceinline__ float bf_lo(unsigned w) { return __uint_as_float(w << 16); }
; __device__ __forceinline__ float bf_hi(unsigned w) { return __uint_as_float(w & 0xffff0000u); }
; __device__ __forceinline__ unsigned f2bf(float f) { unsigned u = __builtin_bit_cast(unsigned, f); return (u + 0x7fffu + ((u >> 16) & 1u)) >> 16; }
; __device__ __forceinline__ void gate_unit(LAS unsigned char* lds, bf16_t* Zg, int ch, const bf16_t* wsb, const float* ln_g, const float* ln_b, const float* b_s, bool dostore = true) {
;     ...
;         for (int i = 0; i < 4; ++i) { const int p = tid + 512 * i, q = p >> 4, c = p & 15; const int col = g * 128 + c * 8;
;             const u32x4 w = *(const u32x4*)(Zc + (size_t)q * ZLD + COL_VB + col);
;             const float mean = stats[q * 2], rstd = stats[q * 2 + 1];
;             const f32x4 g0 = *(const f32x4*)(ln_g + col), g1 = *(const f32x4*)(ln_g + col + 4), b0 = *(const f32x4*)(ln_b + col), b1 = *(const f32x4*)(ln_b + col + 4);
;             float v[8] = {bf_lo(w.x), bf_hi(w.x), bf_lo(w.y), bf_hi(w.y), bf_lo(w.z), bf_hi(w.z), bf_lo(w.w), bf_hi(w.w)};
;             const float gg[8] = {g0.x, g0.y, g0.z, g0.w, g1.x, g1.y, g1.z, g1.w}, bb[8] = {b0.x, b0.y, b0.z, b0.w, b1.x, b1.y, b1.z, b1.w};
; #pragma unroll
;             for (int e = 0; e < 8; ++e) vnT[(c * 8 + e) * 136 + q] = (bf16_t)f2bf((v[e] - mean) * rstd * gg[e] + bb[e]); }
	v_lshlrev_b32_e32 v24, 16, v18
	v_and_b32_e32 v25, 0xffff0000, v18
	v_sub_f32_e32 v24, v24, v22
	v_sub_f32_e32 v25, v25, v22
	v_mul_f32_e32 v24, v23, v24
	v_mul_f32_e32 v25, v23, v25
	v_fma_f32 v24, v10, v24, v14
	v_fma_f32 v25, v11, v25, v15
	v_cvt_pk_bf16_f32 v28, v24, v25
	v_lshlrev_b32_e32 v24, 16, v19
	v_and_b32_e32 v25, 0xffff0000, v19
	v_sub_f32_e32 v24, v24, v22
	v_sub_f32_e32 v25, v25, v22
	v_mul_f32_e32 v24, v23, v24
	v_mul_f32_e32 v25, v23, v25
	v_fma_f32 v24, v12, v24, v16
	v_fma_f32 v25, v13, v25, v17
	v_cvt_pk_bf16_f32 v29, v24, v25
	v_lshlrev_b32_e32 v24, 16, v20
	v_and_b32_e32 v25, 0xffff0000, v20
	v_sub_f32_e32 v24, v24, v22
	v_sub_f32_e32 v25, v25, v22
	v_mul_f32_e32 v24, v23, v24
	v_mul_f32_e32 v25, v23, v25
	v_fma_f32 v24, v2, v24, v6
	v_fma_f32 v25, v3, v25, v7
	v_cvt_pk_bf16_f32 v30, v24, v25
	v_lshlrev_b32_e32 v24, 16, v21
	v_and_b32_e32 v25, 0xffff0000, v21
	v_sub_f32_e32 v24, v24, v22
	v_sub_f32_e32 v25, v25, v22
	v_mul_f32_e32 v24, v23, v24
	v_mul_f32_e32 v25, v23, v25
	v_fma_f32 v24, v4, v24, v8
	v_fma_f32 v25, v5, v25, v9
	v_cvt_pk_bf16_f32 v31, v24, v25
	ds_write_b128 v176, v[28:31] offset:2048
	s_waitcnt vmcnt(22) lgkmcnt(3)
	v_lshlrev_b32_e32 v24, 16, v80
	v_and_b32_e32 v25, 0xffff0000, v80
	v_sub_f32_e32 v24, v24, v180
	v_sub_f32_e32 v25, v25, v180
	v_mul_f32_e32 v24, v181, v24
	v_mul_f32_e32 v25, v181, v25
	v_fma_f32 v24, v10, v24, v14
	v_fma_f32 v25, v11, v25, v15
	v_cvt_pk_bf16_f32 v28, v24, v25
	v_lshlrev_b32_e32 v24, 16, v81
	v_and_b32_e32 v25, 0xffff0000, v81
	v_sub_f32_e32 v24, v24, v180
	v_sub_f32_e32 v25, v25, v180
	v_mul_f32_e32 v24, v181, v24
	v_mul_f32_e32 v25, v181, v25
	v_fma_f32 v24, v12, v24, v16
	v_fma_f32 v25, v13, v25, v17
	v_cvt_pk_bf16_f32 v29, v24, v25
	v_lshlrev_b32_e32 v24, 16, v82
	v_and_b32_e32 v25, 0xffff0000, v82
	v_sub_f32_e32 v24, v24, v180
	v_sub_f32_e32 v25, v25, v180
	v_mul_f32_e32 v24, v181, v24
	v_mul_f32_e32 v25, v181, v25
	v_fma_f32 v24, v2, v24, v6
	v_fma_f32 v25, v3, v25, v7
	v_cvt_pk_bf16_f32 v30, v24, v25
	v_lshlrev_b32_e32 v24, 16, v83
	v_and_b32_e32 v25, 0xffff0000, v83
	v_sub_f32_e32 v24, v24, v180
	v_sub_f32_e32 v25, v25, v180
	v_mul_f32_e32 v24, v181, v24
	v_mul_f32_e32 v25, v181, v25
	v_fma_f32 v24, v4, v24, v8
	v_fma_f32 v25, v5, v25, v9
	v_cvt_pk_bf16_f32 v31, v24, v25
	ds_write_b128 v176, v[28:31] offset:11264
	s_waitcnt vmcnt(21) lgkmcnt(3)
	v_lshlrev_b32_e32 v24, 16, v84
	v_and_b32_e32 v25, 0xffff0000, v84
	v_sub_f32_e32 v24, v24, v182
	v_sub_f32_e32 v25, v25, v182
	v_mul_f32_e32 v24, v183, v24
	v_mul_f32_e32 v25, v183, v25
	v_fma_f32 v24, v10, v24, v14
	v_fma_f32 v25, v11, v25, v15
	v_cvt_pk_bf16_f32 v28, v24, v25
	v_lshlrev_b32_e32 v24, 16, v85
	v_and_b32_e32 v25, 0xffff0000, v85
	v_sub_f32_e32 v24, v24, v182
	v_sub_f32_e32 v25, v25, v182
	v_mul_f32_e32 v24, v183, v24
	v_mul_f32_e32 v25, v183, v25
	v_fma_f32 v24, v12, v24, v16
	v_fma_f32 v25, v13, v25, v17
	v_cvt_pk_bf16_f32 v29, v24, v25
	v_lshlrev_b32_e32 v24, 16, v86
	v_and_b32_e32 v25, 0xffff0000, v86
	v_sub_f32_e32 v24, v24, v182
	v_sub_f32_e32 v25, v25, v182
	v_mul_f32_e32 v24, v183, v24
	v_mul_f32_e32 v25, v183, v25
	v_fma_f32 v24, v2, v24, v6
	v_fma_f32 v25, v3, v25, v7
	v_cvt_pk_bf16_f32 v30, v24, v25
	v_lshlrev_b32_e32 v24, 16, v87
	v_and_b32_e32 v25, 0xffff0000, v87
	v_sub_f32_e32 v24, v24, v182
	v_sub_f32_e32 v25, v25, v182
	v_mul_f32_e32 v24, v183, v24
	v_mul_f32_e32 v25, v183, v25
	v_fma_f32 v24, v4, v24, v8
	v_fma_f32 v25, v5, v25, v9
	v_cvt_pk_bf16_f32 v31, v24, v25
	ds_write_b128 v176, v[28:31] offset:20480
	s_waitcnt vmcnt(20) lgkmcnt(3)
	v_lshlrev_b32_e32 v24, 16, v88
	v_and_b32_e32 v25, 0xffff0000, v88
	v_sub_f32_e32 v24, v24, v184
	v_sub_f32_e32 v25, v25, v184
	v_mul_f32_e32 v24, v185, v24
	v_mul_f32_e32 v25, v185, v25
	v_fma_f32 v24, v10, v24, v14
	v_fma_f32 v25, v11, v25, v15
	v_cvt_pk_bf16_f32 v28, v24, v25
	v_lshlrev_b32_e32 v24, 16, v89
	v_and_b32_e32 v25, 0xffff0000, v89
	v_sub_f32_e32 v24, v24, v184
	v_sub_f32_e32 v25, v25, v184
	v_mul_f32_e32 v24, v185, v24
	v_mul_f32_e32 v25, v185, v25
	v_fma_f32 v24, v12, v24, v16
	v_fma_f32 v25, v13, v25, v17
	v_cvt_pk_bf16_f32 v29, v24, v25
	v_lshlrev_b32_e32 v24, 16, v90
	v_and_b32_e32 v25, 0xffff0000, v90
	v_sub_f32_e32 v24, v24, v184
	v_sub_f32_e32 v25, v25, v184
	v_mul_f32_e32 v24, v185, v24
	v_mul_f32_e32 v25, v185, v25
	v_fma_f32 v24, v2, v24, v6
	v_fma_f32 v25, v3, v25, v7
	v_cvt_pk_bf16_f32 v30, v24, v25
	v_lshlrev_b32_e32 v24, 16, v91
	v_and_b32_e32 v25, 0xffff0000, v91
	v_sub_f32_e32 v24, v24, v184
	v_sub_f32_e32 v25, v25, v184
	v_mul_f32_e32 v24, v185, v24
	v_mul_f32_e32 v25, v185, v25
	v_fma_f32 v24, v4, v24, v8
	v_fma_f32 v25, v5, v25, v9
	v_cvt_pk_bf16_f32 v31, v24, v25
	ds_write_b128 v176, v[28:31] offset:29696
	s_add_u32 s4, s4, 0x100
	s_addc_u32 s5, s5, 0
	s_cmpk_lg_i32 s4, 0x800
	s_waitcnt lgkmcnt(0)
	s_barrier
; #define LAS __attribute__((address_space(3)))
; __device__ __forceinline__ int crow(int r, int hi) { return (r & 3) + 8 * (r >> 2) + 4 * hi; }
; __device__ __forceinline__ void gate_unit(LAS unsigned char* lds, bf16_t* Zg, int ch, const bf16_t* wsb, const float* ln_g, const float* ln_b, const float* b_s, bool dostore = true) {
;     ...
;         f32x16 acc[2]; acc[0] = f32x16{}; acc[1] = f32x16{};
;         const bf16_t* ap = wsb + (size_t)g * 16384 + (32 * pt + r32) * 128 + 8 * hi;
; #pragma unroll
;         for (int ks = 0; ks < 8; ++ks) { const bf16x8 a = *(const bf16x8*)(ap + 16 * ks);
; #pragma unroll
;             for (int j = 0; j < 2; ++j) { const bf16x8 b = *(const LAS bf16x8*)(vnT + (32 * (kt0 + j) + r32) * 136 + 16 * ks + 8 * hi);
;                 acc[j] = __builtin_amdgcn_mfma_f32_32x32x16_bf16(a, b, acc[j], 0, 0, 0); } }
;         LAS float* st = (LAS float*)(lds + 40960);
; #pragma unroll
;         for (int j = 0; j < 2; ++j)
; #pragma unroll
;             for (int r = 0; r < 16; ++r) { const int p = 32 * pt + crow(r, hi); st[p * 132 + 32 * (kt0 + j) + r32] = acc[j][r] + b_s[g * 128 + p]; }
	ds_read_b64_tr_b16 v[68:69], v177 offset:2048
	ds_read_b64_tr_b16 v[70:71], v177 offset:3200
	ds_read_b64_tr_b16 v[72:73], v177 offset:2112
	ds_read_b64_tr_b16 v[74:75], v177 offset:3264
	ds_read_b64_tr_b16 v[76:77], v177 offset:6656
	ds_read_b64_tr_b16 v[78:79], v177 offset:7808
	ds_read_b64_tr_b16 v[186:187], v177 offset:6720
	ds_read_b64_tr_b16 v[188:189], v177 offset:7872
	s_waitcnt vmcnt(12) lgkmcnt(4)
	v_mfma_f32_32x32x16_bf16 v[18:33], v[92:95], v[68:71], 0
	v_mfma_f32_32x32x16_bf16 v[2:17], v[92:95], v[72:75], 0
	ds_read_b64_tr_b16 v[68:69], v177 offset:11264
	ds_read_b64_tr_b16 v[70:71], v177 offset:12416
	ds_read_b64_tr_b16 v[72:73], v177 offset:11328
	ds_read_b64_tr_b16 v[74:75], v177 offset:12480
	s_waitcnt lgkmcnt(4)
	v_mfma_f32_32x32x16_bf16 v[18:33], v[96:99], v[76:79], v[18:33]
	v_mfma_f32_32x32x16_bf16 v[2:17], v[96:99], v[186:189], v[2:17]
	ds_read_b64_tr_b16 v[76:77], v177 offset:15872
	ds_read_b64_tr_b16 v[78:79], v177 offset:17024
	ds_read_b64_tr_b16 v[186:187], v177 offset:15936
	ds_read_b64_tr_b16 v[188:189], v177 offset:17088
	s_waitcnt lgkmcnt(4)
	v_mfma_f32_32x32x16_bf16 v[18:33], v[100:103], v[68:71], v[18:33]
	v_mfma_f32_32x32x16_bf16 v[2:17], v[100:103], v[72:75], v[2:17]
	ds_read_b64_tr_b16 v[68:69], v177 offset:20480
	ds_read_b64_tr_b16 v[70:71], v177 offset:21632
	ds_read_b64_tr_b16 v[72:73], v177 offset:20544
	ds_read_b64_tr_b16 v[74:75], v177 offset:21696
	s_waitcnt lgkmcnt(4)
	v_mfma_f32_32x32x16_bf16 v[18:33], v[104:107], v[76:79], v[18:33]
	v_mfma_f32_32x32x16_bf16 v[2:17], v[104:107], v[186:189], v[2:17]
	ds_read_b64_tr_b16 v[76:77], v177 offset:25088
	ds_read_b64_tr_b16 v[78:79], v177 offset:26240
	ds_read_b64_tr_b16 v[186:187], v177 offset:25152
	ds_read_b64_tr_b16 v[188:189], v177 offset:26304
	s_waitcnt lgkmcnt(4)
	v_mfma_f32_32x32x16_bf16 v[18:33], v[108:111], v[68:71], v[18:33]
	v_mfma_f32_32x32x16_bf16 v[2:17], v[108:111], v[72:75], v[2:17]
	ds_read_b64_tr_b16 v[68:69], v177 offset:29696
	ds_read_b64_tr_b16 v[70:71], v177 offset:30848
	ds_read_b64_tr_b16 v[72:73], v177 offset:29760
	ds_read_b64_tr_b16 v[74:75], v177 offset:30912
	s_waitcnt lgkmcnt(4)
	v_mfma_f32_32x32x16_bf16 v[18:33], v[112:115], v[76:79], v[18:33]
	v_mfma_f32_32x32x16_bf16 v[2:17], v[112:115], v[186:189], v[2:17]
	ds_read_b64_tr_b16 v[76:77], v177 offset:34304
	ds_read_b64_tr_b16 v[78:79], v177 offset:35456
	ds_read_b64_tr_b16 v[186:187], v177 offset:34368
	ds_read_b64_tr_b16 v[188:189], v177 offset:35520
	s_waitcnt lgkmcnt(4)
	v_mfma_f32_32x32x16_bf16 v[18:33], v[116:119], v[68:71], v[18:33]
	v_mfma_f32_32x32x16_bf16 v[2:17], v[116:119], v[72:75], v[2:17]
	s_waitcnt lgkmcnt(0)
	v_mfma_f32_32x32x16_bf16 v[18:33], v[120:123], v[76:79], v[18:33]
	v_mfma_f32_32x32x16_bf16 v[2:17], v[120:123], v[186:189], v[2:17]
	v_lshl_add_u64 v[44:45], v[44:45], 0, s[16:17]
	v_add_u32_e32 v35, 0xa000, v65
	v_add_u32_e32 v34, 0x80, v34
	s_waitcnt vmcnt(11)
	s_nop 7
	v_add_f32_e32 v18, v18, v126
	v_add_f32_e32 v19, v19, v127
	ds_write2_b32 v35, v18, v19 offset1:132
	v_add_f32_e32 v18, v20, v128
	v_add_f32_e32 v19, v21, v129
	v_add_u32_e32 v20, 0xa400, v65
	ds_write2_b32 v20, v18, v19 offset0:8 offset1:140
	v_add_u32_e32 v35, 0xb000, v65
	v_add_f32_e32 v2, v2, v126
	v_add_f32_e32 v3, v3, v127
	s_waitcnt vmcnt(10)
	v_add_f32_e32 v22, v22, v130
	v_add_f32_e32 v23, v23, v131
	ds_write2_b32 v35, v22, v23 offset0:32 offset1:164
	v_add_f32_e32 v22, v24, v132
	v_add_f32_e32 v23, v25, v133
	v_add_u32_e32 v24, 0xb400, v65
	ds_write2_b32 v24, v22, v23 offset0:40 offset1:172
	v_add_u32_e32 v35, 0xc000, v65
	s_waitcnt vmcnt(9)
	v_add_f32_e32 v26, v26, v134
	v_add_f32_e32 v27, v27, v135
	ds_write2_b32 v35, v26, v27 offset0:64 offset1:196
	v_add_f32_e32 v26, v28, v136
	v_add_f32_e32 v27, v29, v137
	v_add_u32_e32 v28, 0xc400, v65
	ds_write2_b32 v28, v26, v27 offset0:72 offset1:204
	v_add_u32_e32 v35, 0xd000, v65
	s_waitcnt vmcnt(8)
	v_add_f32_e32 v30, v30, v138
	v_add_f32_e32 v31, v31, v139
	ds_write2_b32 v35, v30, v31 offset0:96 offset1:228
	v_add_f32_e32 v30, v32, v140
	v_add_f32_e32 v31, v33, v141
	v_add_u32_e32 v32, 0xd400, v65
	ds_write2_b32 v32, v30, v31 offset0:104 offset1:236
	v_add_u32_e32 v30, 0xa000, v66
	ds_write2_b32 v30, v2, v3 offset1:132
	v_add_f32_e32 v2, v4, v128
	v_add_f32_e32 v3, v5, v129
	v_add_u32_e32 v4, 0xa400, v66
	ds_write2_b32 v4, v2, v3 offset0:8 offset1:140
	v_add_f32_e32 v2, v6, v130
	v_add_f32_e32 v3, v7, v131
	v_add_u32_e32 v4, 0xb000, v66
	ds_write2_b32 v4, v2, v3 offset0:32 offset1:164
	v_add_f32_e32 v2, v8, v132
	v_add_f32_e32 v3, v9, v133
	v_add_u32_e32 v4, 0xb400, v66
	ds_write2_b32 v4, v2, v3 offset0:40 offset1:172
	v_add_f32_e32 v2, v10, v134
	v_add_f32_e32 v3, v11, v135
	v_add_u32_e32 v4, 0xc000, v66
	ds_write2_b32 v4, v2, v3 offset0:64 offset1:196
	v_add_f32_e32 v2, v12, v136
	v_add_f32_e32 v3, v13, v137
	v_add_u32_e32 v4, 0xc400, v66
	ds_write2_b32 v4, v2, v3 offset0:72 offset1:204
	v_add_f32_e32 v2, v14, v138
	v_add_f32_e32 v3, v15, v139
	v_add_u32_e32 v4, 0xd000, v66
	v_add_co_u32_e32 v6, vcc, s10, v58
	ds_write2_b32 v4, v2, v3 offset0:96 offset1:228
	v_add_f32_e32 v2, v16, v140
	v_add_f32_e32 v3, v17, v141
	v_add_u32_e32 v4, 0xd400, v66
	v_addc_co_u32_e32 v7, vcc, 0, v59, vcc
	ds_write2_b32 v4, v2, v3 offset0:104 offset1:236
	s_waitcnt lgkmcnt(0)
	s_barrier
; __device__ __forceinline__ unsigned cvt_pk_bf16(float lo, float hi) { f32x2 v = {lo, hi}; bf16x2_t b = __builtin_convertvector(v, bf16x2_t); return __builtin_bit_cast(unsigned, b); }
; __device__ __forceinline__ float bf_lo(unsigned w) { return __uint_as_float(w << 16); }
; __device__ __forceinline__ float bf_hi(unsigned w) { return __uint_as_float(w & 0xffff0000u); }
; __device__ __forceinline__ float sigmoidf_fast(float x) { return __builtin_amdgcn_rcpf(1.0f + __builtin_amdgcn_exp2f(-1.4426950408889634f * x)); }
; #define LAS __attribute__((address_space(3)))
; __device__ __forceinline__ void gate_unit(LAS unsigned char* lds, bf16_t* Zg, int ch, const bf16_t* wsb, const float* ln_g, const float* ln_b, const float* b_s, bool dostore = true) {
;     ...
; #pragma unroll
;         for (int i = 0; i < 4; ++i) { const int p = (tid >> 4) + 32 * i, c8 = (tid & 15) * 8; bf16_t* zr = Zc + (size_t)p * ZLD + g * 128 + c8;
;             const u32x4 uw = *(const u32x4*)(zr + COL_U), gw = *(const u32x4*)(zr + COL_GB);
;             const f32x4 s0 = *(const LAS f32x4*)(st + p * 132 + c8), s1 = *(const LAS f32x4*)(st + p * 132 + c8 + 4);
;             const float sv[8] = {s0.x, s0.y, s0.z, s0.w, s1.x, s1.y, s1.z, s1.w}; u32x4 ow;
; #pragma unroll
;             for (int e = 0; e < 4; ++e) { const float u0 = bf_lo(uw[e]), u1 = bf_hi(uw[e]), g0 = bf_lo(gw[e]), g1 = bf_hi(gw[e]);
;                 ow[e] = cvt_pk_bf16(u0 * sv[2 * e] * g0 * sigmoidf_fast(g0), u1 * sv[2 * e + 1] * g1 * sigmoidf_fast(g1)); }
;             if (dostore) *(u32x4*)(zr + COL_U) = ow; }
	s_waitcnt vmcnt(6)
	v_mov_b64_e32 v[2:3], v[142:143]
	v_mov_b64_e32 v[4:5], v[144:145]
	v_add_u32_e32 v24, v37, v39
	v_mov_b64_e32 v[6:7], v[146:147]
	v_mov_b64_e32 v[8:9], v[148:149]
	ds_read_b128 v[10:13], v24 offset:40960
	ds_read_b128 v[14:17], v24 offset:40976
	s_mov_b32 s10, 0x5a92000
	v_lshlrev_b32_e32 v18, 16, v2
	v_and_b32_e32 v19, 0xffff0000, v2
	v_lshlrev_b32_e32 v20, 16, v6
	v_mul_f32_e32 v2, 0xbfb8aa3b, v20
	v_exp_f32_e32 v2, v2
	v_and_b32_e32 v21, 0xffff0000, v6
	s_waitcnt lgkmcnt(1)
	v_pk_mul_f32 v[10:11], v[10:11], v[18:19]
	v_lshlrev_b32_e32 v6, 16, v7
	v_add_f32_e32 v2, 1.0, v2
	v_rcp_f32_e32 v22, v2
	v_mul_f32_e32 v2, 0xbfb8aa3b, v21
	v_exp_f32_e32 v2, v2
	v_pk_mul_f32 v[10:11], v[10:11], v[20:21]
	v_and_b32_e32 v7, 0xffff0000, v7
	v_add_f32_e32 v2, 1.0, v2
	v_rcp_f32_e32 v23, v2
	s_nop 0
	v_pk_mul_f32 v[10:11], v[10:11], v[22:23]
	s_nop 0
	v_cvt_pk_bf16_f32 v2, v10, v11
	v_lshlrev_b32_e32 v10, 16, v3
	v_and_b32_e32 v11, 0xffff0000, v3
	v_mul_f32_e32 v3, 0xbfb8aa3b, v6
	v_exp_f32_e32 v3, v3
	v_pk_mul_f32 v[10:11], v[12:13], v[10:11]
	v_add_f32_e32 v3, 1.0, v3
	v_rcp_f32_e32 v18, v3
	v_mul_f32_e32 v3, 0xbfb8aa3b, v7
	v_exp_f32_e32 v3, v3
	v_pk_mul_f32 v[10:11], v[10:11], v[6:7]
	v_add_f32_e32 v3, 1.0, v3
	v_rcp_f32_e32 v19, v3
	s_nop 0
	v_pk_mul_f32 v[6:7], v[10:11], v[18:19]
	v_lshlrev_b32_e32 v10, 16, v8
	v_cvt_pk_bf16_f32 v3, v6, v7
	v_lshlrev_b32_e32 v6, 16, v4
	v_and_b32_e32 v7, 0xffff0000, v4
	v_mul_f32_e32 v4, 0xbfb8aa3b, v10
	v_exp_f32_e32 v4, v4
	v_and_b32_e32 v11, 0xffff0000, v8
	s_waitcnt lgkmcnt(0)
	v_pk_mul_f32 v[6:7], v[14:15], v[6:7]
	v_lshlrev_b32_e32 v8, 16, v9
	v_add_f32_e32 v4, 1.0, v4
	v_rcp_f32_e32 v12, v4
	v_mul_f32_e32 v4, 0xbfb8aa3b, v11
	v_exp_f32_e32 v4, v4
	v_pk_mul_f32 v[6:7], v[6:7], v[10:11]
	v_and_b32_e32 v9, 0xffff0000, v9
	v_add_co_u32_e32 v18, vcc, s10, v58
	v_add_f32_e32 v4, 1.0, v4
	v_rcp_f32_e32 v13, v4
	v_addc_co_u32_e32 v19, vcc, 0, v59, vcc
	s_mov_b32 s10, 0x5a93000
	v_pk_mul_f32 v[6:7], v[6:7], v[12:13]
	s_nop 0
	v_cvt_pk_bf16_f32 v4, v6, v7
	v_lshlrev_b32_e32 v6, 16, v5
	v_and_b32_e32 v7, 0xffff0000, v5
	v_mul_f32_e32 v5, 0xbfb8aa3b, v8
	v_exp_f32_e32 v5, v5
	v_pk_mul_f32 v[6:7], v[16:17], v[6:7]
	v_add_f32_e32 v5, 1.0, v5
	v_rcp_f32_e32 v10, v5
	v_mul_f32_e32 v5, 0xbfb8aa3b, v9
	v_exp_f32_e32 v5, v5
	v_pk_mul_f32 v[6:7], v[6:7], v[8:9]
	v_add_f32_e32 v5, 1.0, v5
	v_rcp_f32_e32 v11, v5
	s_nop 0
	v_pk_mul_f32 v[6:7], v[6:7], v[10:11]
	s_nop 0
	v_cvt_pk_bf16_f32 v5, v6, v7
	v_add_co_u32_e32 v6, vcc, s10, v58
	global_store_dwordx4 v[60:61], v[2:5], off
	s_nop 0
	v_addc_co_u32_e32 v7, vcc, 0, v59, vcc
	s_waitcnt vmcnt(5)
	v_mov_b64_e32 v[2:3], v[150:151]
	v_mov_b64_e32 v[4:5], v[152:153]
	s_nop 0
	v_mov_b64_e32 v[6:7], v[154:155]
	v_mov_b64_e32 v[8:9], v[156:157]
	ds_read_b128 v[10:13], v24 offset:57856
	ds_read_b128 v[14:17], v24 offset:57872
	s_mov_b32 s10, 0x5b22000
	v_lshlrev_b32_e32 v20, 16, v2
	v_lshlrev_b32_e32 v22, 16, v6
	v_and_b32_e32 v21, 0xffff0000, v2
	v_mul_f32_e32 v2, 0xbfb8aa3b, v22
	v_exp_f32_e32 v2, v2
	v_and_b32_e32 v23, 0xffff0000, v6
	s_waitcnt lgkmcnt(1)
	v_pk_mul_f32 v[10:11], v[10:11], v[20:21]
	v_lshlrev_b32_e32 v6, 16, v7
	v_add_f32_e32 v2, 1.0, v2
	v_rcp_f32_e32 v24, v2
	v_mul_f32_e32 v2, 0xbfb8aa3b, v23
	v_exp_f32_e32 v2, v2
	v_pk_mul_f32 v[10:11], v[10:11], v[22:23]
	v_and_b32_e32 v7, 0xffff0000, v7
	v_add_f32_e32 v2, 1.0, v2
	v_rcp_f32_e32 v25, v2
	s_nop 0
	v_pk_mul_f32 v[10:11], v[10:11], v[24:25]
	s_nop 0
	v_cvt_pk_bf16_f32 v2, v10, v11
	v_lshlrev_b32_e32 v10, 16, v3
	v_and_b32_e32 v11, 0xffff0000, v3
	v_mul_f32_e32 v3, 0xbfb8aa3b, v6
	v_exp_f32_e32 v3, v3
	v_pk_mul_f32 v[10:11], v[12:13], v[10:11]
	v_add_f32_e32 v3, 1.0, v3
	v_rcp_f32_e32 v20, v3
	v_mul_f32_e32 v3, 0xbfb8aa3b, v7
	v_exp_f32_e32 v3, v3
	v_pk_mul_f32 v[10:11], v[10:11], v[6:7]
	v_add_f32_e32 v3, 1.0, v3
	v_rcp_f32_e32 v21, v3
	s_nop 0
	v_pk_mul_f32 v[6:7], v[10:11], v[20:21]
	v_lshlrev_b32_e32 v10, 16, v8
	v_cvt_pk_bf16_f32 v3, v6, v7
	v_lshlrev_b32_e32 v6, 16, v4
	v_and_b32_e32 v7, 0xffff0000, v4
	v_mul_f32_e32 v4, 0xbfb8aa3b, v10
	v_exp_f32_e32 v4, v4
	v_and_b32_e32 v11, 0xffff0000, v8
	s_waitcnt lgkmcnt(0)
	v_pk_mul_f32 v[6:7], v[14:15], v[6:7]
	v_lshlrev_b32_e32 v8, 16, v9
	v_add_f32_e32 v4, 1.0, v4
	v_rcp_f32_e32 v12, v4
	v_mul_f32_e32 v4, 0xbfb8aa3b, v11
	v_exp_f32_e32 v4, v4
	v_pk_mul_f32 v[6:7], v[6:7], v[10:11]
	v_and_b32_e32 v9, 0xffff0000, v9
	v_add_f32_e32 v4, 1.0, v4
	v_rcp_f32_e32 v13, v4
	s_nop 0
	v_pk_mul_f32 v[6:7], v[6:7], v[12:13]
	s_nop 0
	v_cvt_pk_bf16_f32 v4, v6, v7
	v_lshlrev_b32_e32 v6, 16, v5
	v_and_b32_e32 v7, 0xffff0000, v5
	v_mul_f32_e32 v5, 0xbfb8aa3b, v8
	v_exp_f32_e32 v5, v5
	v_pk_mul_f32 v[6:7], v[16:17], v[6:7]
	v_add_f32_e32 v5, 1.0, v5
	v_rcp_f32_e32 v10, v5
	v_mul_f32_e32 v5, 0xbfb8aa3b, v9
	v_exp_f32_e32 v5, v5
	v_pk_mul_f32 v[6:7], v[6:7], v[8:9]
	v_add_f32_e32 v5, 1.0, v5
	v_rcp_f32_e32 v11, v5
	s_nop 0
	v_pk_mul_f32 v[6:7], v[6:7], v[10:11]
	s_nop 0
	v_cvt_pk_bf16_f32 v5, v6, v7
	global_store_dwordx4 v[18:19], v[2:5], off
	v_add_co_u32_e32 v18, vcc, s10, v58
	s_mov_b32 s10, 0x5b23000
	s_nop 0
	v_addc_co_u32_e32 v19, vcc, 0, v59, vcc
	v_add_co_u32_e32 v6, vcc, s10, v58
	s_mov_b32 s10, 0x5bb2000
	s_nop 0
	v_addc_co_u32_e32 v7, vcc, 0, v59, vcc
	s_waitcnt vmcnt(4)
; __device__ __forceinline__ unsigned cvt_pk_bf16(float lo, float hi) { f32x2 v = {lo, hi}; bf16x2_t b = __builtin_convertvector(v, bf16x2_t); return __builtin_bit_cast(unsigned, b); }
; __device__ __forceinline__ float bf_lo(unsigned w) { return __uint_as_float(w << 16); }
; __device__ __forceinline__ float bf_hi(unsigned w) { return __uint_as_float(w & 0xffff0000u); }
; __device__ __forceinline__ float sigmoidf_fast(float x) { return __builtin_amdgcn_rcpf(1.0f + __builtin_amdgcn_exp2f(-1.4426950408889634f * x)); }
; #define LAS __attribute__((address_space(3)))
; __device__ __forceinline__ void gate_unit(LAS unsigned char* lds, bf16_t* Zg, int ch, const bf16_t* wsb, const float* ln_g, const float* ln_b, const float* b_s, bool dostore = true) {
;     ...
; #pragma unroll
;         for (int i = 0; i < 4; ++i) { const int p = (tid >> 4) + 32 * i, c8 = (tid & 15) * 8; bf16_t* zr = Zc + (size_t)p * ZLD + g * 128 + c8;
;             const u32x4 uw = *(const u32x4*)(zr + COL_U), gw = *(const u32x4*)(zr + COL_GB);
;             const f32x4 s0 = *(const LAS f32x4*)(st + p * 132 + c8), s1 = *(const LAS f32x4*)(st + p * 132 + c8 + 4);
;             const float sv[8] = {s0.x, s0.y, s0.z, s0.w, s1.x, s1.y, s1.z, s1.w}; u32x4 ow;
; #pragma unroll
;             for (int e = 0; e < 4; ++e) { const float u0 = bf_lo(uw[e]), u1 = bf_hi(uw[e]), g0 = bf_lo(gw[e]), g1 = bf_hi(gw[e]);
;                 ow[e] = cvt_pk_bf16(u0 * sv[2 * e] * g0 * sigmoidf_fast(g0), u1 * sv[2 * e + 1] * g1 * sigmoidf_fast(g1)); }
;             if (dostore) *(u32x4*)(zr + COL_U) = ow; }
;         __syncthreads();
;     }
	v_mov_b64_e32 v[2:3], v[158:159]
	v_mov_b64_e32 v[4:5], v[160:161]
	s_nop 0
	v_mov_b64_e32 v[6:7], v[162:163]
	v_mov_b64_e32 v[8:9], v[164:165]
	ds_read_b128 v[10:13], v67 offset:40960
	ds_read_b128 v[14:17], v67 offset:40976
	v_lshlrev_b32_e32 v20, 16, v2
	v_lshlrev_b32_e32 v22, 16, v6
	v_and_b32_e32 v21, 0xffff0000, v2
	v_mul_f32_e32 v2, 0xbfb8aa3b, v22
	v_exp_f32_e32 v2, v2
	v_and_b32_e32 v23, 0xffff0000, v6
	s_waitcnt lgkmcnt(1)
	v_pk_mul_f32 v[10:11], v[10:11], v[20:21]
	v_lshlrev_b32_e32 v6, 16, v7
	v_add_f32_e32 v2, 1.0, v2
	v_rcp_f32_e32 v24, v2
	v_mul_f32_e32 v2, 0xbfb8aa3b, v23
	v_exp_f32_e32 v2, v2
	v_pk_mul_f32 v[10:11], v[10:11], v[22:23]
	v_and_b32_e32 v7, 0xffff0000, v7
	v_add_f32_e32 v2, 1.0, v2
	v_rcp_f32_e32 v25, v2
	s_nop 0
	v_pk_mul_f32 v[10:11], v[10:11], v[24:25]
	s_nop 0
	v_cvt_pk_bf16_f32 v2, v10, v11
	v_lshlrev_b32_e32 v10, 16, v3
	v_and_b32_e32 v11, 0xffff0000, v3
	v_mul_f32_e32 v3, 0xbfb8aa3b, v6
	v_exp_f32_e32 v3, v3
	v_pk_mul_f32 v[10:11], v[12:13], v[10:11]
	v_add_f32_e32 v3, 1.0, v3
	v_rcp_f32_e32 v20, v3
	v_mul_f32_e32 v3, 0xbfb8aa3b, v7
	v_exp_f32_e32 v3, v3
	v_pk_mul_f32 v[10:11], v[10:11], v[6:7]
	v_add_f32_e32 v3, 1.0, v3
	v_rcp_f32_e32 v21, v3
	s_nop 0
	v_pk_mul_f32 v[6:7], v[10:11], v[20:21]
	v_lshlrev_b32_e32 v10, 16, v8
	v_cvt_pk_bf16_f32 v3, v6, v7
	v_lshlrev_b32_e32 v6, 16, v4
	v_and_b32_e32 v7, 0xffff0000, v4
	v_mul_f32_e32 v4, 0xbfb8aa3b, v10
	v_exp_f32_e32 v4, v4
	v_and_b32_e32 v11, 0xffff0000, v8
	s_waitcnt lgkmcnt(0)
	v_pk_mul_f32 v[6:7], v[14:15], v[6:7]
	v_lshlrev_b32_e32 v8, 16, v9
	v_add_f32_e32 v4, 1.0, v4
	v_rcp_f32_e32 v12, v4
	v_mul_f32_e32 v4, 0xbfb8aa3b, v11
	v_exp_f32_e32 v4, v4
	v_pk_mul_f32 v[6:7], v[6:7], v[10:11]
	v_and_b32_e32 v9, 0xffff0000, v9
	v_add_f32_e32 v4, 1.0, v4
	v_rcp_f32_e32 v13, v4
	s_nop 0
	v_pk_mul_f32 v[6:7], v[6:7], v[12:13]
	s_nop 0
	v_cvt_pk_bf16_f32 v4, v6, v7
	v_lshlrev_b32_e32 v6, 16, v5
	v_and_b32_e32 v7, 0xffff0000, v5
	v_mul_f32_e32 v5, 0xbfb8aa3b, v8
	v_exp_f32_e32 v5, v5
	v_pk_mul_f32 v[6:7], v[16:17], v[6:7]
	v_add_f32_e32 v5, 1.0, v5
	v_rcp_f32_e32 v10, v5
	v_mul_f32_e32 v5, 0xbfb8aa3b, v9
	v_exp_f32_e32 v5, v5
	v_pk_mul_f32 v[6:7], v[6:7], v[8:9]
	v_add_f32_e32 v5, 1.0, v5
	v_rcp_f32_e32 v11, v5
	s_nop 0
	v_pk_mul_f32 v[6:7], v[6:7], v[10:11]
	s_nop 0
	v_cvt_pk_bf16_f32 v5, v6, v7
	global_store_dwordx4 v[18:19], v[2:5], off
	v_add_co_u32_e32 v18, vcc, s10, v58
	s_mov_b32 s10, 0x5bb3000
	s_nop 0
	v_addc_co_u32_e32 v19, vcc, 0, v59, vcc
	v_add_co_u32_e32 v6, vcc, s10, v58
	s_nop 1
	v_addc_co_u32_e32 v7, vcc, 0, v59, vcc
	s_waitcnt vmcnt(3)
	v_mov_b64_e32 v[2:3], v[166:167]
	v_mov_b64_e32 v[4:5], v[168:169]
	s_nop 0
	v_mov_b64_e32 v[6:7], v[170:171]
	v_mov_b64_e32 v[8:9], v[172:173]
	ds_read_b128 v[10:13], v67 offset:57856
	ds_read_b128 v[14:17], v67 offset:57872
	v_lshlrev_b32_e32 v20, 16, v2
	v_lshlrev_b32_e32 v22, 16, v6
	v_and_b32_e32 v21, 0xffff0000, v2
	v_mul_f32_e32 v2, 0xbfb8aa3b, v22
	v_exp_f32_e32 v2, v2
	v_and_b32_e32 v23, 0xffff0000, v6
	s_waitcnt lgkmcnt(1)
	v_pk_mul_f32 v[10:11], v[10:11], v[20:21]
	v_lshlrev_b32_e32 v6, 16, v7
	v_add_f32_e32 v2, 1.0, v2
	v_rcp_f32_e32 v24, v2
	v_mul_f32_e32 v2, 0xbfb8aa3b, v23
	v_exp_f32_e32 v2, v2
	v_pk_mul_f32 v[10:11], v[10:11], v[22:23]
	v_and_b32_e32 v7, 0xffff0000, v7
	v_add_f32_e32 v2, 1.0, v2
	v_rcp_f32_e32 v25, v2
	s_nop 0
	v_pk_mul_f32 v[10:11], v[10:11], v[24:25]
	s_nop 0
	v_cvt_pk_bf16_f32 v2, v10, v11
	v_lshlrev_b32_e32 v10, 16, v3
	v_and_b32_e32 v11, 0xffff0000, v3
	v_mul_f32_e32 v3, 0xbfb8aa3b, v6
	v_exp_f32_e32 v3, v3
	v_pk_mul_f32 v[10:11], v[12:13], v[10:11]
	v_add_f32_e32 v3, 1.0, v3
	v_rcp_f32_e32 v20, v3
	v_mul_f32_e32 v3, 0xbfb8aa3b, v7
	v_exp_f32_e32 v3, v3
	v_pk_mul_f32 v[10:11], v[10:11], v[6:7]
	v_add_f32_e32 v3, 1.0, v3
	v_rcp_f32_e32 v21, v3
	s_nop 0
	v_pk_mul_f32 v[6:7], v[10:11], v[20:21]
	v_lshlrev_b32_e32 v10, 16, v8
	v_cvt_pk_bf16_f32 v3, v6, v7
	v_lshlrev_b32_e32 v6, 16, v4
	v_and_b32_e32 v7, 0xffff0000, v4
	v_mul_f32_e32 v4, 0xbfb8aa3b, v10
	v_exp_f32_e32 v4, v4
	v_and_b32_e32 v11, 0xffff0000, v8
	s_waitcnt lgkmcnt(0)
	v_pk_mul_f32 v[6:7], v[14:15], v[6:7]
	v_lshlrev_b32_e32 v8, 16, v9
	v_add_f32_e32 v4, 1.0, v4
	v_rcp_f32_e32 v12, v4
	v_mul_f32_e32 v4, 0xbfb8aa3b, v11
	v_exp_f32_e32 v4, v4
	v_pk_mul_f32 v[6:7], v[6:7], v[10:11]
	v_and_b32_e32 v9, 0xffff0000, v9
	v_add_f32_e32 v4, 1.0, v4
	v_rcp_f32_e32 v13, v4
	s_nop 0
	v_pk_mul_f32 v[6:7], v[6:7], v[12:13]
	s_nop 0
	v_cvt_pk_bf16_f32 v4, v6, v7
	v_lshlrev_b32_e32 v6, 16, v5
	v_and_b32_e32 v7, 0xffff0000, v5
	v_mul_f32_e32 v5, 0xbfb8aa3b, v8
	v_exp_f32_e32 v5, v5
	v_pk_mul_f32 v[6:7], v[16:17], v[6:7]
	v_add_f32_e32 v5, 1.0, v5
	v_rcp_f32_e32 v10, v5
	v_mul_f32_e32 v5, 0xbfb8aa3b, v9
	v_exp_f32_e32 v5, v5
	v_pk_mul_f32 v[6:7], v[6:7], v[8:9]
	v_add_f32_e32 v5, 1.0, v5
	v_rcp_f32_e32 v11, v5
	s_nop 0
	v_pk_mul_f32 v[6:7], v[6:7], v[10:11]
	s_nop 0
	v_cvt_pk_bf16_f32 v5, v6, v7
	global_store_dwordx4 v[18:19], v[2:5], off
	s_barrier
	s_cbranch_scc1 .LBB0_183
	s_add_i32 s15, s15, s3
	s_add_u32 s12, s12, s24
	s_addc_u32 s13, s13, s18
	s_add_u32 s8, s8, s24
	s_addc_u32 s9, s9, s18
	s_add_u32 s6, s6, s24
	s_addc_u32 s7, s7, s18
	s_cmpk_gt_i32 s15, 0xff
	s_cbranch_scc0 .LBB0_178
